# phase 5 EpiMix hand-written: bias loaded once, slot loads software-pipelined with counted vmcnt, grouped transcendentals; same f32 ops per element
# speedup vs baseline: 1.0121x; 1.0075x over previous
; #define PG8_WAIT_V(n) asm volatile("s_waitcnt vmcnt(" #n ")" ::: "memory")
; #define PG8_BAR __builtin_amdgcn_s_barrier()
; #define PG8_WAIT_V(n) asm volatile("s_waitcnt vmcnt(" #n ")" ::: "memory")
; #define PG8_BAR __builtin_amdgcn_s_barrier()
; DI void gemm_phase_p5(LAS unsigned char* lds, const Unit u, const bf16_t* hb, const bf16_t* xn, const bf16_t* wtm, const bf16_t* wtp,
;                       char* scr, bf16_t* mixed, const float* bmerge) {
;     ...
;     unsigned ldc = cur.isP ? ldH : ldX;
;     size_t hsc = cur.isP ? hsH : hsX;
;     PG8_STAGE2(PG8_SB(0, 0), cur.B, PG8_ROWB, ldX); PG8_STAGE2(PG8_SA(0, 0), cur.A, rowA, ldc);
;     PG8_STAGE2(PG8_SB(0, 1), cur.B + hstepB, PG8_ROWB, ldX); PG8_STAGE2(PG8_SA(0, 1), cur.A + hsc, rowA, ldc);
;     if (wr == 1) PG8_BAR;
;     PG8_WAIT_V(4); PG8_BAR;
;     PG8_STAGE2(PG8_SB(1, 0), cur.B + kstep, PG8_ROWB, ldX); PG8_STAGE2(PG8_SA(1, 0), cur.A + kstep, rowA, ldc);
;     PG8_STAGE2(PG8_SB(1, 1), cur.B + hstepB + kstep, PG8_ROWB, ldX);
;     PG8_WAIT_V(6); PG8_BAR;
;     ...
;         if (!has_next) break;
; #pragma unroll
;         for (int a = 0; a < 2; ++a)
; #pragma unroll
;             for (int b = 0; b < 2; ++b)
; #pragma unroll
;                 for (int m = 0; m < 4; ++m)
; #pragma unroll
;                     for (int n = 0; n < 2; ++n) acc[a][b][m][n] = (f32x4){0.f, 0.f, 0.f, 0.f};
;         cur = nxt; ldc = ldn; hsc = hsn;
.LBB0_928:
	s_waitcnt lgkmcnt(0)
	s_add_u32 s70, s20, s4
	s_addc_u32 s71, s21, s5
	s_lshl_b32 s0, s40, 5
	v_and_b32_e32 v8, 48, v7
	s_and_b32 s20, s0, 0x60
	v_lshlrev_b32_e32 v9, 6, v7
	s_movk_i32 s0, 0x3c0
	v_lshlrev_b32_e32 v7, 2, v7
	v_and_or_b32 v8, v9, s0, v8
	s_lshl_b32 s0, s20, 7
	v_and_b32_e32 v7, 32, v7
	v_bitop3_b32 v183, s0, v8, v7 bitop3:0xf6
	s_lshl_b32 s0, s10, 13
	v_bitop3_b32 v7, v8, s0, v7 bitop3:0xde
	v_lshl_add_u64 v[8:9], v[2:3], 0, s[16:17]
	s_add_i32 m0, s66, 0x18000
	s_waitcnt vmcnt(4)
	s_barrier
	global_load_lds_dwordx4 v[8:9], off
	v_lshl_add_u64 v[8:9], v[2:3], 0, s[28:29]
	s_add_i32 m0, s66, 0x1a000
	s_add_i32 s72, s66, 0x8000
	global_load_lds_dwordx4 v[8:9], off
	v_lshl_add_u64 v[8:9], v[4:5], 0, s[16:17]
	s_mov_b32 m0, s72
	s_mov_b64 s[0:1], 0x78080
	s_add_i32 s73, s66, 0xa000
	global_load_lds_dwordx4 v[8:9], off
	v_lshl_add_u64 v[4:5], v[4:5], 0, s[0:1]
	s_mov_b32 m0, s73
	s_lshl_b32 s11, s10, 6
	global_load_lds_dwordx4 v[4:5], off
	v_lshl_add_u64 v[4:5], v[2:3], 0, s[18:19]
	s_add_i32 m0, s66, 0x1c000
	v_lshl_add_u64 v[2:3], v[2:3], 0, s[30:31]
	global_load_lds_dwordx4 v[4:5], off
	s_add_i32 m0, s66, 0x1e000
	s_add_u32 s74, s56, s7
	global_load_lds_dwordx4 v[2:3], off
	s_addc_u32 s75, s57, s6
	s_lshl_b64 s[0:1], s[34:35], 19
	s_add_u32 s40, s54, s0
	s_waitcnt vmcnt(6)
	s_addc_u32 s41, s55, s1
	s_lshl_b32 s0, s34, 8
	s_mov_b32 s10, 8
	s_add_i32 s35, s11, s0
	s_lshl_b32 s0, s12, 8
	s_mov_b32 s79, 1
	v_and_b32_e32 v0, 1, v0
	v_lshlrev_b32_e32 v2, 1, v6
	s_or_b32 s76, s0, s20
	v_lshl_add_u32 v182, v0, 6, v2
	s_movk_i32 s80, 0x1e00
	s_mov_b64 s[48:49], 0xf0000
	s_mov_b32 s77, 0
	v_add_u32_e32 v210, 0, v7
	s_mov_b32 s78, s79
	s_mov_b32 s20, s10
	s_mov_b64 s[44:45], s[50:51]
	s_mov_b64 s[42:43], s[36:37]
	s_barrier
	s_branch .LBB0_931
.LBB0_930:
	s_add_i32 s0, s77, 1
	s_cmp_lg_u32 s77, 5
	s_mov_b32 s77, s0
	s_mov_b64 s[48:49], s[46:47]
	s_mov_b32 s80, s21
	s_mov_b64 s[36:37], s[42:43]
	s_mov_b64 s[50:51], s[44:45]
	s_mov_b32 s10, s20
	s_mov_b32 s79, s78
	s_cbranch_scc0 .LBB0_974

; DI unsigned pack2(float a, float b) { fv2 v = {a, b}; return __builtin_bit_cast(unsigned, __builtin_convertvector(v, bfv2)); }
; DI float bflo(unsigned u) { return __uint_as_float(u << 16); }
; DI float bfhi(unsigned u) { return __uint_as_float(u & 0xffff0000u); }
; DI float sigmoidf_(float x) { return __builtin_amdgcn_rcpf(1.f + __expf(-x)); }
;   DI void operator()(const f32x4 (&acc)[2][2][4][2], const Unit& u, int wr, int wc, int fr, int fq) const {
;     const int row0 = u.pm * BM + wr * 64 + fr, col0 = u.pn * BM + wc * 32 + 8 * fq;
;     const char* sb = scr; asm volatile("" : "+s"(sb));
;     const unsigned toff = (unsigned)tidx() * 16u;
; #pragma unroll
;     for (int ai = 0; ai < 2; ++ai)
; #pragma unroll
;       for (int mp = 0; mp < 2; ++mp) {
;         u32x4 pv[2][2], ov[2][2];
;         f32x4 bv[2][2];
; #pragma unroll
;         for (int bj = 0; bj < 2; ++bj)
; #pragma unroll
;           for (int n = 0; n < 2; ++n) bv[bj][n] = *(const f32x4*)(bias + col0 + bj * HALF + 4 * n);
; #pragma unroll
;         for (int mm = 0; mm < 2; ++mm)
; #pragma unroll
;           for (int bj = 0; bj < 2; ++bj) {
;             const int m = mp * 2 + mm;
;             pv[mm][bj] = *(const u32x4*)(sb + (size_t)(((ai * 4 + m) * 2 + bj) * 8192) + toff);
;             ov[mm][bj] = (u32x4){0u, 0u, 0u, 0u};
;             if (!first) ov[mm][bj] = *(const u32x4*)(mixed + (size_t)(row0 + ai * HALF + m * 16) * 1024 + col0 + bj * HALF);
;           }
; #pragma unroll
;         for (int mm = 0; mm < 2; ++mm)
; #pragma unroll
;           for (int bj = 0; bj < 2; ++bj) {
;             const int m = mp * 2 + mm;
;             const f32x4 g0 = acc[ai][bj][m][0] + bv[bj][0], g1 = acc[ai][bj][m][1] + bv[bj][1];
;             const u32x4 p_ = pv[mm][bj], o_ = ov[mm][bj];
;             u32x4 w;
;             w.x = pack2(bflo(o_.x) + sigmoidf_(g0[0]) * bflo(p_.x), bfhi(o_.x) + sigmoidf_(g0[1]) * bfhi(p_.x));
;             w.y = pack2(bflo(o_.y) + sigmoidf_(g0[2]) * bflo(p_.y), bfhi(o_.y) + sigmoidf_(g0[3]) * bfhi(p_.y));
;             w.z = pack2(bflo(o_.z) + sigmoidf_(g1[0]) * bflo(p_.z), bfhi(o_.z) + sigmoidf_(g1[1]) * bfhi(p_.z));
;             w.w = pack2(bflo(o_.w) + sigmoidf_(g1[2]) * bflo(p_.w), bfhi(o_.w) + sigmoidf_(g1[3]) * bfhi(p_.w));
;             *(u32x4*)(mixed + (size_t)(row0 + ai * HALF + m * 16) * 1024 + col0 + bj * HALF) = w;
;           }
;       }
.LBB0_941:
.LBB0_942:
	s_lshl_b32 s0, s77, 9
	s_mov_b32 s1, s89
	s_and_b32 s0, s0, 0x7ffffc00
	s_lshl_b64 s[0:1], s[0:1], 2
	s_add_u32 s0, s70, s0
	s_addc_u32 s1, s71, s1
	v_lshrrev_b32_e32 v146, 1, v201
	v_and_b32_e32 v146, 24, v146
	v_or_b32_e32 v147, s76, v146
	v_lshlrev_b32_e32 v148, 2, v147
	global_load_dwordx4 v[130:133], v148, s[0:1]
	global_load_dwordx4 v[134:137], v148, s[0:1] offset:16
	global_load_dwordx4 v[138:141], v148, s[0:1] offset:512
	global_load_dwordx4 v[142:145], v148, s[0:1] offset:528
	v_lshlrev_b32_e32 v0, 4, v201
	v_and_b32_e32 v212, 15, v201
	v_lshlrev_b32_e32 v212, 11, v212
	v_lshl_add_u32 v212, v146, 1, v212
	s_cmp_lt_u32 s77, 2
	s_mov_b32 s36, 0x01000c0c
	s_mov_b32 s37, 0x03020c0c
	s_cselect_b32 s36, 0x0c0c0c0c, s36
	s_cselect_b32 s37, 0x0c0c0c0c, s37
	v_and_b32_e32 v149, 0xfffffeff, v0
	s_cselect_b64 vcc, -1, 0
	v_cndmask_b32_e32 v213, v212, v149, vcc
	s_mov_b64 s[6:7], s[8:9]
	s_lshl_b32 s98, s35, 11
	s_lshl_b32 s99, s76, 1
	s_add_u32 s98, s98, s99
	s_add_u32 s98, s2, s98
	s_addc_u32 s99, s3, 0
	s_mov_b64 s[100:101], s[98:99]
	global_load_dwordx4 v[166:169], v0, s[6:7]
	s_cmp_lt_u32 s77, 2
	s_cselect_b32 s0, s6, s98
	s_cselect_b32 s1, s7, s99
	global_load_dwordx4 v[170:173], v213, s[0:1]
	s_add_u32 s6, s6, 0x2000
	s_addc_u32 s7, s7, 0
	global_load_dwordx4 v[174:177], v0, s[6:7]
	s_cmp_lt_u32 s77, 2
	s_cselect_b32 s0, s6, s98
	s_cselect_b32 s1, s7, s99
	global_load_dwordx4 v[184:187], v213, s[0:1] offset:256
	s_add_u32 s6, s6, 0x2000
	s_addc_u32 s7, s7, 0
	s_add_u32 s98, s98, 0x8000
	s_addc_u32 s99, s99, 0
	global_load_dwordx4 v[188:191], v0, s[6:7]
	s_cmp_lt_u32 s77, 2
	s_cselect_b32 s0, s6, s98
	s_cselect_b32 s1, s7, s99
	global_load_dwordx4 v[192:195], v213, s[0:1]
	s_add_u32 s6, s6, 0x2000
	s_addc_u32 s7, s7, 0
	s_waitcnt vmcnt(6)
	v_pk_add_f32 v[126:127], v[126:127], v[130:131]
	v_pk_add_f32 v[128:129], v[128:129], v[132:133]
	v_pk_add_f32 v[122:123], v[122:123], v[134:135]
	v_pk_add_f32 v[124:125], v[124:125], v[136:137]
	v_mul_f32_e32 v146, 0xbfb8aa3b, v126
	v_mul_f32_e32 v147, 0xbfb8aa3b, v127
	v_mul_f32_e32 v148, 0xbfb8aa3b, v128
	v_mul_f32_e32 v149, 0xbfb8aa3b, v129
	v_mul_f32_e32 v150, 0xbfb8aa3b, v122
	v_mul_f32_e32 v151, 0xbfb8aa3b, v123
	v_mul_f32_e32 v152, 0xbfb8aa3b, v124
	v_mul_f32_e32 v153, 0xbfb8aa3b, v125
	v_exp_f32_e32 v146, v146
	v_exp_f32_e32 v147, v147
	v_exp_f32_e32 v148, v148
	v_exp_f32_e32 v149, v149
	v_exp_f32_e32 v150, v150
	v_exp_f32_e32 v151, v151
	v_exp_f32_e32 v152, v152
	v_exp_f32_e32 v153, v153
	s_waitcnt vmcnt(4)
	v_lshlrev_b32_e32 v126, 16, v166
	v_and_b32_e32 v127, 0xffff0000, v166
	v_lshlrev_b32_e32 v128, 16, v167
	v_and_b32_e32 v129, 0xffff0000, v167
	v_lshlrev_b32_e32 v122, 16, v168
	v_and_b32_e32 v123, 0xffff0000, v168
	v_lshlrev_b32_e32 v124, 16, v169
	v_and_b32_e32 v125, 0xffff0000, v169
	v_add_f32_e32 v146, 1.0, v146
	v_add_f32_e32 v147, 1.0, v147
	v_add_f32_e32 v148, 1.0, v148
	v_add_f32_e32 v149, 1.0, v149
	v_add_f32_e32 v150, 1.0, v150
	v_add_f32_e32 v151, 1.0, v151
	v_add_f32_e32 v152, 1.0, v152
	v_add_f32_e32 v153, 1.0, v153
	v_rcp_f32_e32 v146, v146
	v_rcp_f32_e32 v147, v147
	v_rcp_f32_e32 v148, v148
	v_rcp_f32_e32 v149, v149
	v_rcp_f32_e32 v150, v150
	v_rcp_f32_e32 v151, v151
	v_rcp_f32_e32 v152, v152
	v_rcp_f32_e32 v153, v153
	v_perm_b32 v154, v170, v170, s36
	v_perm_b32 v155, v170, v170, s37
	v_perm_b32 v156, v171, v171, s36
	v_perm_b32 v157, v171, v171, s37
	v_perm_b32 v158, v172, v172, s36
	v_perm_b32 v159, v172, v172, s37
	v_perm_b32 v160, v173, v173, s36
	v_perm_b32 v161, v173, v173, s37
	v_pk_fma_f32 v[146:147], v[146:147], v[126:127], v[154:155]
	v_pk_fma_f32 v[148:149], v[148:149], v[128:129], v[156:157]
	v_pk_fma_f32 v[150:151], v[150:151], v[122:123], v[158:159]
	v_pk_fma_f32 v[152:153], v[152:153], v[124:125], v[160:161]
	v_cvt_pk_bf16_f32 v162, v146, v147
	v_cvt_pk_bf16_f32 v163, v148, v149
	v_cvt_pk_bf16_f32 v164, v150, v151
	v_cvt_pk_bf16_f32 v165, v152, v153
	global_store_dwordx4 v212, v[162:165], s[100:101]
	global_load_dwordx4 v[196:199], v0, s[6:7]
	s_cmp_lt_u32 s77, 2
	s_cselect_b32 s0, s6, s98
	s_cselect_b32 s1, s7, s99
	global_load_dwordx4 v[166:169], v213, s[0:1] offset:256
	s_add_u32 s6, s6, 0x2000
	s_addc_u32 s7, s7, 0
	s_add_u32 s98, s98, 0x8000
	s_addc_u32 s99, s99, 0
	global_load_dwordx4 v[170:173], v0, s[6:7]
	s_cmp_lt_u32 s77, 2
	s_cselect_b32 s0, s6, s98
	s_cselect_b32 s1, s7, s99
	global_load_dwordx4 v[126:129], v213, s[0:1]
	s_add_u32 s6, s6, 0x2000
	s_addc_u32 s7, s7, 0
	v_pk_add_f32 v[118:119], v[118:119], v[138:139]
	v_pk_add_f32 v[120:121], v[120:121], v[140:141]
	v_pk_add_f32 v[114:115], v[114:115], v[142:143]
	v_pk_add_f32 v[116:117], v[116:117], v[144:145]
	v_mul_f32_e32 v146, 0xbfb8aa3b, v118
	v_mul_f32_e32 v147, 0xbfb8aa3b, v119
	v_mul_f32_e32 v148, 0xbfb8aa3b, v120
	v_mul_f32_e32 v149, 0xbfb8aa3b, v121
	v_mul_f32_e32 v150, 0xbfb8aa3b, v114
	v_mul_f32_e32 v151, 0xbfb8aa3b, v115
	v_mul_f32_e32 v152, 0xbfb8aa3b, v116
	v_mul_f32_e32 v153, 0xbfb8aa3b, v117
	v_exp_f32_e32 v146, v146
	v_exp_f32_e32 v147, v147
	v_exp_f32_e32 v148, v148
	v_exp_f32_e32 v149, v149
	v_exp_f32_e32 v150, v150
	v_exp_f32_e32 v151, v151
	v_exp_f32_e32 v152, v152
	v_exp_f32_e32 v153, v153
	s_waitcnt vmcnt(7)
; DI unsigned pack2(float a, float b) { fv2 v = {a, b}; return __builtin_bit_cast(unsigned, __builtin_convertvector(v, bfv2)); }
; DI float bflo(unsigned u) { return __uint_as_float(u << 16); }
; DI float bfhi(unsigned u) { return __uint_as_float(u & 0xffff0000u); }
; DI float sigmoidf_(float x) { return __builtin_amdgcn_rcpf(1.f + __expf(-x)); }
;   DI void operator()(const f32x4 (&acc)[2][2][4][2], const Unit& u, int wr, int wc, int fr, int fq) const {
;     ...
; #pragma unroll
;         for (int mm = 0; mm < 2; ++mm)
; #pragma unroll
;           for (int bj = 0; bj < 2; ++bj) {
;             const int m = mp * 2 + mm;
;             const f32x4 g0 = acc[ai][bj][m][0] + bv[bj][0], g1 = acc[ai][bj][m][1] + bv[bj][1];
;             const u32x4 p_ = pv[mm][bj], o_ = ov[mm][bj];
;             u32x4 w;
;             w.x = pack2(bflo(o_.x) + sigmoidf_(g0[0]) * bflo(p_.x), bfhi(o_.x) + sigmoidf_(g0[1]) * bfhi(p_.x));
;             w.y = pack2(bflo(o_.y) + sigmoidf_(g0[2]) * bflo(p_.y), bfhi(o_.y) + sigmoidf_(g0[3]) * bfhi(p_.y));
;             w.z = pack2(bflo(o_.z) + sigmoidf_(g1[0]) * bflo(p_.z), bfhi(o_.z) + sigmoidf_(g1[1]) * bfhi(p_.z));
;             w.w = pack2(bflo(o_.w) + sigmoidf_(g1[2]) * bflo(p_.w), bfhi(o_.w) + sigmoidf_(g1[3]) * bfhi(p_.w));
;             *(u32x4*)(mixed + (size_t)(row0 + ai * HALF + m * 16) * 1024 + col0 + bj * HALF) = w;
;           }
;       }
	v_lshlrev_b32_e32 v118, 16, v174
	v_and_b32_e32 v119, 0xffff0000, v174
	v_lshlrev_b32_e32 v120, 16, v175
	v_and_b32_e32 v121, 0xffff0000, v175
	v_lshlrev_b32_e32 v114, 16, v176
	v_and_b32_e32 v115, 0xffff0000, v176
	v_lshlrev_b32_e32 v116, 16, v177
	v_and_b32_e32 v117, 0xffff0000, v177
	v_add_f32_e32 v146, 1.0, v146
	v_add_f32_e32 v147, 1.0, v147
	v_add_f32_e32 v148, 1.0, v148
	v_add_f32_e32 v149, 1.0, v149
	v_add_f32_e32 v150, 1.0, v150
	v_add_f32_e32 v151, 1.0, v151
	v_add_f32_e32 v152, 1.0, v152
	v_add_f32_e32 v153, 1.0, v153
	v_rcp_f32_e32 v146, v146
	v_rcp_f32_e32 v147, v147
	v_rcp_f32_e32 v148, v148
	v_rcp_f32_e32 v149, v149
	v_rcp_f32_e32 v150, v150
	v_rcp_f32_e32 v151, v151
	v_rcp_f32_e32 v152, v152
	v_rcp_f32_e32 v153, v153
	v_perm_b32 v154, v184, v184, s36
	v_perm_b32 v155, v184, v184, s37
	v_perm_b32 v156, v185, v185, s36
	v_perm_b32 v157, v185, v185, s37
	v_perm_b32 v158, v186, v186, s36
	v_perm_b32 v159, v186, v186, s37
	v_perm_b32 v160, v187, v187, s36
	v_perm_b32 v161, v187, v187, s37
	v_pk_fma_f32 v[146:147], v[146:147], v[118:119], v[154:155]
	v_pk_fma_f32 v[148:149], v[148:149], v[120:121], v[156:157]
	v_pk_fma_f32 v[150:151], v[150:151], v[114:115], v[158:159]
	v_pk_fma_f32 v[152:153], v[152:153], v[116:117], v[160:161]
	v_cvt_pk_bf16_f32 v162, v146, v147
	v_cvt_pk_bf16_f32 v163, v148, v149
	v_cvt_pk_bf16_f32 v164, v150, v151
	v_cvt_pk_bf16_f32 v165, v152, v153
	global_store_dwordx4 v212, v[162:165], s[100:101] offset:256
	s_add_u32 s100, s100, 0x8000
	s_addc_u32 s101, s101, 0
	global_load_dwordx4 v[122:125], v0, s[6:7]
	s_cmp_lt_u32 s77, 2
	s_cselect_b32 s0, s6, s98
	s_cselect_b32 s1, s7, s99
	global_load_dwordx4 v[174:177], v213, s[0:1] offset:256
	s_add_u32 s6, s6, 0x2000
	s_addc_u32 s7, s7, 0
	s_add_u32 s98, s98, 0x8000
	s_addc_u32 s99, s99, 0
	global_load_dwordx4 v[184:187], v0, s[6:7]
	s_cmp_lt_u32 s77, 2
	s_cselect_b32 s0, s6, s98
	s_cselect_b32 s1, s7, s99
	global_load_dwordx4 v[118:121], v213, s[0:1]
	s_add_u32 s6, s6, 0x2000
	s_addc_u32 s7, s7, 0
	v_pk_add_f32 v[110:111], v[110:111], v[130:131]
	v_pk_add_f32 v[112:113], v[112:113], v[132:133]
	v_pk_add_f32 v[106:107], v[106:107], v[134:135]
	v_pk_add_f32 v[108:109], v[108:109], v[136:137]
	v_mul_f32_e32 v146, 0xbfb8aa3b, v110
	v_mul_f32_e32 v147, 0xbfb8aa3b, v111
	v_mul_f32_e32 v148, 0xbfb8aa3b, v112
	v_mul_f32_e32 v149, 0xbfb8aa3b, v113
	v_mul_f32_e32 v150, 0xbfb8aa3b, v106
	v_mul_f32_e32 v151, 0xbfb8aa3b, v107
	v_mul_f32_e32 v152, 0xbfb8aa3b, v108
	v_mul_f32_e32 v153, 0xbfb8aa3b, v109
	v_exp_f32_e32 v146, v146
	v_exp_f32_e32 v147, v147
	v_exp_f32_e32 v148, v148
	v_exp_f32_e32 v149, v149
	v_exp_f32_e32 v150, v150
	v_exp_f32_e32 v151, v151
	v_exp_f32_e32 v152, v152
	v_exp_f32_e32 v153, v153
	s_waitcnt vmcnt(10)
	v_lshlrev_b32_e32 v110, 16, v188
	v_and_b32_e32 v111, 0xffff0000, v188
	v_lshlrev_b32_e32 v112, 16, v189
	v_and_b32_e32 v113, 0xffff0000, v189
	v_lshlrev_b32_e32 v106, 16, v190
	v_and_b32_e32 v107, 0xffff0000, v190
	v_lshlrev_b32_e32 v108, 16, v191
	v_and_b32_e32 v109, 0xffff0000, v191
	v_add_f32_e32 v146, 1.0, v146
	v_add_f32_e32 v147, 1.0, v147
	v_add_f32_e32 v148, 1.0, v148
	v_add_f32_e32 v149, 1.0, v149
	v_add_f32_e32 v150, 1.0, v150
	v_add_f32_e32 v151, 1.0, v151
	v_add_f32_e32 v152, 1.0, v152
	v_add_f32_e32 v153, 1.0, v153
	v_rcp_f32_e32 v146, v146
	v_rcp_f32_e32 v147, v147
	v_rcp_f32_e32 v148, v148
	v_rcp_f32_e32 v149, v149
	v_rcp_f32_e32 v150, v150
	v_rcp_f32_e32 v151, v151
	v_rcp_f32_e32 v152, v152
	v_rcp_f32_e32 v153, v153
	v_perm_b32 v154, v192, v192, s36
	v_perm_b32 v155, v192, v192, s37
	v_perm_b32 v156, v193, v193, s36
	v_perm_b32 v157, v193, v193, s37
	v_perm_b32 v158, v194, v194, s36
	v_perm_b32 v159, v194, v194, s37
	v_perm_b32 v160, v195, v195, s36
	v_perm_b32 v161, v195, v195, s37
	v_pk_fma_f32 v[146:147], v[146:147], v[110:111], v[154:155]
	v_pk_fma_f32 v[148:149], v[148:149], v[112:113], v[156:157]
	v_pk_fma_f32 v[150:151], v[150:151], v[106:107], v[158:159]
	v_pk_fma_f32 v[152:153], v[152:153], v[108:109], v[160:161]
	v_cvt_pk_bf16_f32 v162, v146, v147
	v_cvt_pk_bf16_f32 v163, v148, v149
	v_cvt_pk_bf16_f32 v164, v150, v151
	v_cvt_pk_bf16_f32 v165, v152, v153
	global_store_dwordx4 v212, v[162:165], s[100:101]
	global_load_dwordx4 v[114:117], v0, s[6:7]
	s_cmp_lt_u32 s77, 2
	s_cselect_b32 s0, s6, s98
	s_cselect_b32 s1, s7, s99
	global_load_dwordx4 v[188:191], v213, s[0:1] offset:256
	s_add_u32 s6, s6, 0x2000
	s_addc_u32 s7, s7, 0
	s_add_u32 s98, s98, 0x28000
	s_addc_u32 s99, s99, 0
	global_load_dwordx4 v[192:195], v0, s[6:7]
	s_cmp_lt_u32 s77, 2
	s_cselect_b32 s0, s6, s98
	s_cselect_b32 s1, s7, s99
	global_load_dwordx4 v[110:113], v213, s[0:1]
	s_add_u32 s6, s6, 0x2000
	s_addc_u32 s7, s7, 0
	v_pk_add_f32 v[102:103], v[102:103], v[138:139]
	v_pk_add_f32 v[104:105], v[104:105], v[140:141]
	v_pk_add_f32 v[98:99], v[98:99], v[142:143]
	v_pk_add_f32 v[100:101], v[100:101], v[144:145]
	v_mul_f32_e32 v146, 0xbfb8aa3b, v102
	v_mul_f32_e32 v147, 0xbfb8aa3b, v103
	v_mul_f32_e32 v148, 0xbfb8aa3b, v104
	v_mul_f32_e32 v149, 0xbfb8aa3b, v105
	v_mul_f32_e32 v150, 0xbfb8aa3b, v98
	v_mul_f32_e32 v151, 0xbfb8aa3b, v99
	v_mul_f32_e32 v152, 0xbfb8aa3b, v100
	v_mul_f32_e32 v153, 0xbfb8aa3b, v101
	v_exp_f32_e32 v146, v146
	v_exp_f32_e32 v147, v147
	v_exp_f32_e32 v148, v148
	v_exp_f32_e32 v149, v149
	v_exp_f32_e32 v150, v150
	v_exp_f32_e32 v151, v151
	v_exp_f32_e32 v152, v152
	v_exp_f32_e32 v153, v153
	s_waitcnt vmcnt(12)
; DI unsigned pack2(float a, float b) { fv2 v = {a, b}; return __builtin_bit_cast(unsigned, __builtin_convertvector(v, bfv2)); }
; DI float bflo(unsigned u) { return __uint_as_float(u << 16); }
; DI float bfhi(unsigned u) { return __uint_as_float(u & 0xffff0000u); }
; DI float sigmoidf_(float x) { return __builtin_amdgcn_rcpf(1.f + __expf(-x)); }
;   DI void operator()(const f32x4 (&acc)[2][2][4][2], const Unit& u, int wr, int wc, int fr, int fq) const {
;     ...
; #pragma unroll
;         for (int mm = 0; mm < 2; ++mm)
; #pragma unroll
;           for (int bj = 0; bj < 2; ++bj) {
;             const int m = mp * 2 + mm;
;             const f32x4 g0 = acc[ai][bj][m][0] + bv[bj][0], g1 = acc[ai][bj][m][1] + bv[bj][1];
;             const u32x4 p_ = pv[mm][bj], o_ = ov[mm][bj];
;             u32x4 w;
;             w.x = pack2(bflo(o_.x) + sigmoidf_(g0[0]) * bflo(p_.x), bfhi(o_.x) + sigmoidf_(g0[1]) * bfhi(p_.x));
;             w.y = pack2(bflo(o_.y) + sigmoidf_(g0[2]) * bflo(p_.y), bfhi(o_.y) + sigmoidf_(g0[3]) * bfhi(p_.y));
;             w.z = pack2(bflo(o_.z) + sigmoidf_(g1[0]) * bflo(p_.z), bfhi(o_.z) + sigmoidf_(g1[1]) * bfhi(p_.z));
;             w.w = pack2(bflo(o_.w) + sigmoidf_(g1[2]) * bflo(p_.w), bfhi(o_.w) + sigmoidf_(g1[3]) * bfhi(p_.w));
;             *(u32x4*)(mixed + (size_t)(row0 + ai * HALF + m * 16) * 1024 + col0 + bj * HALF) = w;
;           }
;       }
	v_lshlrev_b32_e32 v102, 16, v196
	v_and_b32_e32 v103, 0xffff0000, v196
	v_lshlrev_b32_e32 v104, 16, v197
	v_and_b32_e32 v105, 0xffff0000, v197
	v_lshlrev_b32_e32 v98, 16, v198
	v_and_b32_e32 v99, 0xffff0000, v198
	v_lshlrev_b32_e32 v100, 16, v199
	v_and_b32_e32 v101, 0xffff0000, v199
	v_add_f32_e32 v146, 1.0, v146
	v_add_f32_e32 v147, 1.0, v147
	v_add_f32_e32 v148, 1.0, v148
	v_add_f32_e32 v149, 1.0, v149
	v_add_f32_e32 v150, 1.0, v150
	v_add_f32_e32 v151, 1.0, v151
	v_add_f32_e32 v152, 1.0, v152
	v_add_f32_e32 v153, 1.0, v153
	v_rcp_f32_e32 v146, v146
	v_rcp_f32_e32 v147, v147
	v_rcp_f32_e32 v148, v148
	v_rcp_f32_e32 v149, v149
	v_rcp_f32_e32 v150, v150
	v_rcp_f32_e32 v151, v151
	v_rcp_f32_e32 v152, v152
	v_rcp_f32_e32 v153, v153
	v_perm_b32 v154, v166, v166, s36
	v_perm_b32 v155, v166, v166, s37
	v_perm_b32 v156, v167, v167, s36
	v_perm_b32 v157, v167, v167, s37
	v_perm_b32 v158, v168, v168, s36
	v_perm_b32 v159, v168, v168, s37
	v_perm_b32 v160, v169, v169, s36
	v_perm_b32 v161, v169, v169, s37
	v_pk_fma_f32 v[146:147], v[146:147], v[102:103], v[154:155]
	v_pk_fma_f32 v[148:149], v[148:149], v[104:105], v[156:157]
	v_pk_fma_f32 v[150:151], v[150:151], v[98:99], v[158:159]
	v_pk_fma_f32 v[152:153], v[152:153], v[100:101], v[160:161]
	v_cvt_pk_bf16_f32 v162, v146, v147
	v_cvt_pk_bf16_f32 v163, v148, v149
	v_cvt_pk_bf16_f32 v164, v150, v151
	v_cvt_pk_bf16_f32 v165, v152, v153
	global_store_dwordx4 v212, v[162:165], s[100:101] offset:256
	s_add_u32 s100, s100, 0x8000
	s_addc_u32 s101, s101, 0
	global_load_dwordx4 v[106:109], v0, s[6:7]
	s_cmp_lt_u32 s77, 2
	s_cselect_b32 s0, s6, s98
	s_cselect_b32 s1, s7, s99
	global_load_dwordx4 v[196:199], v213, s[0:1] offset:256
	s_add_u32 s6, s6, 0x2000
	s_addc_u32 s7, s7, 0
	s_add_u32 s98, s98, 0x8000
	s_addc_u32 s99, s99, 0
	v_pk_add_f32 v[94:95], v[94:95], v[130:131]
	v_pk_add_f32 v[96:97], v[96:97], v[132:133]
	v_pk_add_f32 v[90:91], v[90:91], v[134:135]
	v_pk_add_f32 v[92:93], v[92:93], v[136:137]
	v_mul_f32_e32 v146, 0xbfb8aa3b, v94
	v_mul_f32_e32 v147, 0xbfb8aa3b, v95
	v_mul_f32_e32 v148, 0xbfb8aa3b, v96
	v_mul_f32_e32 v149, 0xbfb8aa3b, v97
	v_mul_f32_e32 v150, 0xbfb8aa3b, v90
	v_mul_f32_e32 v151, 0xbfb8aa3b, v91
	v_mul_f32_e32 v152, 0xbfb8aa3b, v92
	v_mul_f32_e32 v153, 0xbfb8aa3b, v93
	v_exp_f32_e32 v146, v146
	v_exp_f32_e32 v147, v147
	v_exp_f32_e32 v148, v148
	v_exp_f32_e32 v149, v149
	v_exp_f32_e32 v150, v150
	v_exp_f32_e32 v151, v151
	v_exp_f32_e32 v152, v152
	v_exp_f32_e32 v153, v153
	s_waitcnt vmcnt(13)
	v_lshlrev_b32_e32 v94, 16, v170
	v_and_b32_e32 v95, 0xffff0000, v170
	v_lshlrev_b32_e32 v96, 16, v171
	v_and_b32_e32 v97, 0xffff0000, v171
	v_lshlrev_b32_e32 v90, 16, v172
	v_and_b32_e32 v91, 0xffff0000, v172
	v_lshlrev_b32_e32 v92, 16, v173
	v_and_b32_e32 v93, 0xffff0000, v173
	v_add_f32_e32 v146, 1.0, v146
	v_add_f32_e32 v147, 1.0, v147
	v_add_f32_e32 v148, 1.0, v148
	v_add_f32_e32 v149, 1.0, v149
	v_add_f32_e32 v150, 1.0, v150
	v_add_f32_e32 v151, 1.0, v151
	v_add_f32_e32 v152, 1.0, v152
	v_add_f32_e32 v153, 1.0, v153
	v_rcp_f32_e32 v146, v146
	v_rcp_f32_e32 v147, v147
	v_rcp_f32_e32 v148, v148
	v_rcp_f32_e32 v149, v149
	v_rcp_f32_e32 v150, v150
	v_rcp_f32_e32 v151, v151
	v_rcp_f32_e32 v152, v152
	v_rcp_f32_e32 v153, v153
	v_perm_b32 v154, v126, v126, s36
	v_perm_b32 v155, v126, v126, s37
	v_perm_b32 v156, v127, v127, s36
	v_perm_b32 v157, v127, v127, s37
	v_perm_b32 v158, v128, v128, s36
	v_perm_b32 v159, v128, v128, s37
	v_perm_b32 v160, v129, v129, s36
	v_perm_b32 v161, v129, v129, s37
	v_pk_fma_f32 v[146:147], v[146:147], v[94:95], v[154:155]
	v_pk_fma_f32 v[148:149], v[148:149], v[96:97], v[156:157]
	v_pk_fma_f32 v[150:151], v[150:151], v[90:91], v[158:159]
	v_pk_fma_f32 v[152:153], v[152:153], v[92:93], v[160:161]
	v_cvt_pk_bf16_f32 v162, v146, v147
	v_cvt_pk_bf16_f32 v163, v148, v149
	v_cvt_pk_bf16_f32 v164, v150, v151
	v_cvt_pk_bf16_f32 v165, v152, v153
	global_store_dwordx4 v212, v[162:165], s[100:101]
	global_load_dwordx4 v[166:169], v0, s[6:7]
	s_cmp_lt_u32 s77, 2
	s_cselect_b32 s0, s6, s98
	s_cselect_b32 s1, s7, s99
	global_load_dwordx4 v[102:105], v213, s[0:1]
	s_add_u32 s6, s6, 0x2000
	s_addc_u32 s7, s7, 0
	v_pk_add_f32 v[86:87], v[86:87], v[138:139]
	v_pk_add_f32 v[88:89], v[88:89], v[140:141]
	v_pk_add_f32 v[82:83], v[82:83], v[142:143]
	v_pk_add_f32 v[84:85], v[84:85], v[144:145]
	v_mul_f32_e32 v146, 0xbfb8aa3b, v86
	v_mul_f32_e32 v147, 0xbfb8aa3b, v87
	v_mul_f32_e32 v148, 0xbfb8aa3b, v88
	v_mul_f32_e32 v149, 0xbfb8aa3b, v89
	v_mul_f32_e32 v150, 0xbfb8aa3b, v82
	v_mul_f32_e32 v151, 0xbfb8aa3b, v83
	v_mul_f32_e32 v152, 0xbfb8aa3b, v84
	v_mul_f32_e32 v153, 0xbfb8aa3b, v85
	v_exp_f32_e32 v146, v146
	v_exp_f32_e32 v147, v147
	v_exp_f32_e32 v148, v148
	v_exp_f32_e32 v149, v149
	v_exp_f32_e32 v150, v150
	v_exp_f32_e32 v151, v151
	v_exp_f32_e32 v152, v152
	v_exp_f32_e32 v153, v153
	s_waitcnt vmcnt(13)
; DI unsigned pack2(float a, float b) { fv2 v = {a, b}; return __builtin_bit_cast(unsigned, __builtin_convertvector(v, bfv2)); }
; DI float bflo(unsigned u) { return __uint_as_float(u << 16); }
; DI float bfhi(unsigned u) { return __uint_as_float(u & 0xffff0000u); }
; DI float sigmoidf_(float x) { return __builtin_amdgcn_rcpf(1.f + __expf(-x)); }
;   DI void operator()(const f32x4 (&acc)[2][2][4][2], const Unit& u, int wr, int wc, int fr, int fq) const {
;     ...
; #pragma unroll
;         for (int mm = 0; mm < 2; ++mm)
; #pragma unroll
;           for (int bj = 0; bj < 2; ++bj) {
;             const int m = mp * 2 + mm;
;             const f32x4 g0 = acc[ai][bj][m][0] + bv[bj][0], g1 = acc[ai][bj][m][1] + bv[bj][1];
;             const u32x4 p_ = pv[mm][bj], o_ = ov[mm][bj];
;             u32x4 w;
;             w.x = pack2(bflo(o_.x) + sigmoidf_(g0[0]) * bflo(p_.x), bfhi(o_.x) + sigmoidf_(g0[1]) * bfhi(p_.x));
;             w.y = pack2(bflo(o_.y) + sigmoidf_(g0[2]) * bflo(p_.y), bfhi(o_.y) + sigmoidf_(g0[3]) * bfhi(p_.y));
;             w.z = pack2(bflo(o_.z) + sigmoidf_(g1[0]) * bflo(p_.z), bfhi(o_.z) + sigmoidf_(g1[1]) * bfhi(p_.z));
;             w.w = pack2(bflo(o_.w) + sigmoidf_(g1[2]) * bflo(p_.w), bfhi(o_.w) + sigmoidf_(g1[3]) * bfhi(p_.w));
;             *(u32x4*)(mixed + (size_t)(row0 + ai * HALF + m * 16) * 1024 + col0 + bj * HALF) = w;
;           }
;       }
	v_lshlrev_b32_e32 v86, 16, v122
	v_and_b32_e32 v87, 0xffff0000, v122
	v_lshlrev_b32_e32 v88, 16, v123
	v_and_b32_e32 v89, 0xffff0000, v123
	v_lshlrev_b32_e32 v82, 16, v124
	v_and_b32_e32 v83, 0xffff0000, v124
	v_lshlrev_b32_e32 v84, 16, v125
	v_and_b32_e32 v85, 0xffff0000, v125
	v_add_f32_e32 v146, 1.0, v146
	v_add_f32_e32 v147, 1.0, v147
	v_add_f32_e32 v148, 1.0, v148
	v_add_f32_e32 v149, 1.0, v149
	v_add_f32_e32 v150, 1.0, v150
	v_add_f32_e32 v151, 1.0, v151
	v_add_f32_e32 v152, 1.0, v152
	v_add_f32_e32 v153, 1.0, v153
	v_rcp_f32_e32 v146, v146
	v_rcp_f32_e32 v147, v147
	v_rcp_f32_e32 v148, v148
	v_rcp_f32_e32 v149, v149
	v_rcp_f32_e32 v150, v150
	v_rcp_f32_e32 v151, v151
	v_rcp_f32_e32 v152, v152
	v_rcp_f32_e32 v153, v153
	v_perm_b32 v154, v174, v174, s36
	v_perm_b32 v155, v174, v174, s37
	v_perm_b32 v156, v175, v175, s36
	v_perm_b32 v157, v175, v175, s37
	v_perm_b32 v158, v176, v176, s36
	v_perm_b32 v159, v176, v176, s37
	v_perm_b32 v160, v177, v177, s36
	v_perm_b32 v161, v177, v177, s37
	v_pk_fma_f32 v[146:147], v[146:147], v[86:87], v[154:155]
	v_pk_fma_f32 v[148:149], v[148:149], v[88:89], v[156:157]
	v_pk_fma_f32 v[150:151], v[150:151], v[82:83], v[158:159]
	v_pk_fma_f32 v[152:153], v[152:153], v[84:85], v[160:161]
	v_cvt_pk_bf16_f32 v162, v146, v147
	v_cvt_pk_bf16_f32 v163, v148, v149
	v_cvt_pk_bf16_f32 v164, v150, v151
	v_cvt_pk_bf16_f32 v165, v152, v153
	global_store_dwordx4 v212, v[162:165], s[100:101] offset:256
	s_add_u32 s100, s100, 0x8000
	s_addc_u32 s101, s101, 0
	global_load_dwordx4 v[98:101], v0, s[6:7]
	s_cmp_lt_u32 s77, 2
	s_cselect_b32 s0, s6, s98
	s_cselect_b32 s1, s7, s99
	global_load_dwordx4 v[170:173], v213, s[0:1] offset:256
	s_add_u32 s6, s6, 0x2000
	s_addc_u32 s7, s7, 0
	s_add_u32 s98, s98, 0x8000
	s_addc_u32 s99, s99, 0
	v_pk_add_f32 v[78:79], v[78:79], v[130:131]
	v_pk_add_f32 v[80:81], v[80:81], v[132:133]
	v_pk_add_f32 v[74:75], v[74:75], v[134:135]
	v_pk_add_f32 v[76:77], v[76:77], v[136:137]
	v_mul_f32_e32 v146, 0xbfb8aa3b, v78
	v_mul_f32_e32 v147, 0xbfb8aa3b, v79
	v_mul_f32_e32 v148, 0xbfb8aa3b, v80
	v_mul_f32_e32 v149, 0xbfb8aa3b, v81
	v_mul_f32_e32 v150, 0xbfb8aa3b, v74
	v_mul_f32_e32 v151, 0xbfb8aa3b, v75
	v_mul_f32_e32 v152, 0xbfb8aa3b, v76
	v_mul_f32_e32 v153, 0xbfb8aa3b, v77
	v_exp_f32_e32 v146, v146
	v_exp_f32_e32 v147, v147
	v_exp_f32_e32 v148, v148
	v_exp_f32_e32 v149, v149
	v_exp_f32_e32 v150, v150
	v_exp_f32_e32 v151, v151
	v_exp_f32_e32 v152, v152
	v_exp_f32_e32 v153, v153
	s_waitcnt vmcnt(14)
	v_lshlrev_b32_e32 v78, 16, v184
	v_and_b32_e32 v79, 0xffff0000, v184
	v_lshlrev_b32_e32 v80, 16, v185
	v_and_b32_e32 v81, 0xffff0000, v185
	v_lshlrev_b32_e32 v74, 16, v186
	v_and_b32_e32 v75, 0xffff0000, v186
	v_lshlrev_b32_e32 v76, 16, v187
	v_and_b32_e32 v77, 0xffff0000, v187
	v_add_f32_e32 v146, 1.0, v146
	v_add_f32_e32 v147, 1.0, v147
	v_add_f32_e32 v148, 1.0, v148
	v_add_f32_e32 v149, 1.0, v149
	v_add_f32_e32 v150, 1.0, v150
	v_add_f32_e32 v151, 1.0, v151
	v_add_f32_e32 v152, 1.0, v152
	v_add_f32_e32 v153, 1.0, v153
	v_rcp_f32_e32 v146, v146
	v_rcp_f32_e32 v147, v147
	v_rcp_f32_e32 v148, v148
	v_rcp_f32_e32 v149, v149
	v_rcp_f32_e32 v150, v150
	v_rcp_f32_e32 v151, v151
	v_rcp_f32_e32 v152, v152
	v_rcp_f32_e32 v153, v153
	v_perm_b32 v154, v118, v118, s36
	v_perm_b32 v155, v118, v118, s37
	v_perm_b32 v156, v119, v119, s36
	v_perm_b32 v157, v119, v119, s37
	v_perm_b32 v158, v120, v120, s36
	v_perm_b32 v159, v120, v120, s37
	v_perm_b32 v160, v121, v121, s36
	v_perm_b32 v161, v121, v121, s37
	v_pk_fma_f32 v[146:147], v[146:147], v[78:79], v[154:155]
	v_pk_fma_f32 v[148:149], v[148:149], v[80:81], v[156:157]
	v_pk_fma_f32 v[150:151], v[150:151], v[74:75], v[158:159]
	v_pk_fma_f32 v[152:153], v[152:153], v[76:77], v[160:161]
	v_cvt_pk_bf16_f32 v162, v146, v147
	v_cvt_pk_bf16_f32 v163, v148, v149
	v_cvt_pk_bf16_f32 v164, v150, v151
	v_cvt_pk_bf16_f32 v165, v152, v153
	global_store_dwordx4 v212, v[162:165], s[100:101]
	global_load_dwordx4 v[126:129], v0, s[6:7]
	s_cmp_lt_u32 s77, 2
	s_cselect_b32 s0, s6, s98
	s_cselect_b32 s1, s7, s99
	global_load_dwordx4 v[94:97], v213, s[0:1]
	s_add_u32 s6, s6, 0x2000
	s_addc_u32 s7, s7, 0
	v_pk_add_f32 v[70:71], v[70:71], v[138:139]
	v_pk_add_f32 v[72:73], v[72:73], v[140:141]
	v_pk_add_f32 v[66:67], v[66:67], v[142:143]
	v_pk_add_f32 v[68:69], v[68:69], v[144:145]
	v_mul_f32_e32 v146, 0xbfb8aa3b, v70
	v_mul_f32_e32 v147, 0xbfb8aa3b, v71
	v_mul_f32_e32 v148, 0xbfb8aa3b, v72
	v_mul_f32_e32 v149, 0xbfb8aa3b, v73
	v_mul_f32_e32 v150, 0xbfb8aa3b, v66
	v_mul_f32_e32 v151, 0xbfb8aa3b, v67
	v_mul_f32_e32 v152, 0xbfb8aa3b, v68
	v_mul_f32_e32 v153, 0xbfb8aa3b, v69
	v_exp_f32_e32 v146, v146
	v_exp_f32_e32 v147, v147
	v_exp_f32_e32 v148, v148
	v_exp_f32_e32 v149, v149
	v_exp_f32_e32 v150, v150
	v_exp_f32_e32 v151, v151
	v_exp_f32_e32 v152, v152
	v_exp_f32_e32 v153, v153
	s_waitcnt vmcnt(14)
; DI unsigned pack2(float a, float b) { fv2 v = {a, b}; return __builtin_bit_cast(unsigned, __builtin_convertvector(v, bfv2)); }
; DI float bflo(unsigned u) { return __uint_as_float(u << 16); }
; DI float bfhi(unsigned u) { return __uint_as_float(u & 0xffff0000u); }
; DI float sigmoidf_(float x) { return __builtin_amdgcn_rcpf(1.f + __expf(-x)); }
;   DI void operator()(const f32x4 (&acc)[2][2][4][2], const Unit& u, int wr, int wc, int fr, int fq) const {
;     ...
; #pragma unroll
;         for (int mm = 0; mm < 2; ++mm)
; #pragma unroll
;           for (int bj = 0; bj < 2; ++bj) {
;             const int m = mp * 2 + mm;
;             const f32x4 g0 = acc[ai][bj][m][0] + bv[bj][0], g1 = acc[ai][bj][m][1] + bv[bj][1];
;             const u32x4 p_ = pv[mm][bj], o_ = ov[mm][bj];
;             u32x4 w;
;             w.x = pack2(bflo(o_.x) + sigmoidf_(g0[0]) * bflo(p_.x), bfhi(o_.x) + sigmoidf_(g0[1]) * bfhi(p_.x));
;             w.y = pack2(bflo(o_.y) + sigmoidf_(g0[2]) * bflo(p_.y), bfhi(o_.y) + sigmoidf_(g0[3]) * bfhi(p_.y));
;             w.z = pack2(bflo(o_.z) + sigmoidf_(g1[0]) * bflo(p_.z), bfhi(o_.z) + sigmoidf_(g1[1]) * bfhi(p_.z));
;             w.w = pack2(bflo(o_.w) + sigmoidf_(g1[2]) * bflo(p_.w), bfhi(o_.w) + sigmoidf_(g1[3]) * bfhi(p_.w));
;             *(u32x4*)(mixed + (size_t)(row0 + ai * HALF + m * 16) * 1024 + col0 + bj * HALF) = w;
;           }
;       }
	v_lshlrev_b32_e32 v70, 16, v114
	v_and_b32_e32 v71, 0xffff0000, v114
	v_lshlrev_b32_e32 v72, 16, v115
	v_and_b32_e32 v73, 0xffff0000, v115
	v_lshlrev_b32_e32 v66, 16, v116
	v_and_b32_e32 v67, 0xffff0000, v116
	v_lshlrev_b32_e32 v68, 16, v117
	v_and_b32_e32 v69, 0xffff0000, v117
	v_add_f32_e32 v146, 1.0, v146
	v_add_f32_e32 v147, 1.0, v147
	v_add_f32_e32 v148, 1.0, v148
	v_add_f32_e32 v149, 1.0, v149
	v_add_f32_e32 v150, 1.0, v150
	v_add_f32_e32 v151, 1.0, v151
	v_add_f32_e32 v152, 1.0, v152
	v_add_f32_e32 v153, 1.0, v153
	v_rcp_f32_e32 v146, v146
	v_rcp_f32_e32 v147, v147
	v_rcp_f32_e32 v148, v148
	v_rcp_f32_e32 v149, v149
	v_rcp_f32_e32 v150, v150
	v_rcp_f32_e32 v151, v151
	v_rcp_f32_e32 v152, v152
	v_rcp_f32_e32 v153, v153
	v_perm_b32 v154, v188, v188, s36
	v_perm_b32 v155, v188, v188, s37
	v_perm_b32 v156, v189, v189, s36
	v_perm_b32 v157, v189, v189, s37
	v_perm_b32 v158, v190, v190, s36
	v_perm_b32 v159, v190, v190, s37
	v_perm_b32 v160, v191, v191, s36
	v_perm_b32 v161, v191, v191, s37
	v_pk_fma_f32 v[146:147], v[146:147], v[70:71], v[154:155]
	v_pk_fma_f32 v[148:149], v[148:149], v[72:73], v[156:157]
	v_pk_fma_f32 v[150:151], v[150:151], v[66:67], v[158:159]
	v_pk_fma_f32 v[152:153], v[152:153], v[68:69], v[160:161]
	v_cvt_pk_bf16_f32 v162, v146, v147
	v_cvt_pk_bf16_f32 v163, v148, v149
	v_cvt_pk_bf16_f32 v164, v150, v151
	v_cvt_pk_bf16_f32 v165, v152, v153
	global_store_dwordx4 v212, v[162:165], s[100:101] offset:256
	s_add_u32 s100, s100, 0x28000
	s_addc_u32 s101, s101, 0
	global_load_dwordx4 v[90:93], v0, s[6:7]
	s_cmp_lt_u32 s77, 2
	s_cselect_b32 s0, s6, s98
	s_cselect_b32 s1, s7, s99
	global_load_dwordx4 v[122:125], v213, s[0:1] offset:256
	s_add_u32 s6, s6, 0x2000
	s_addc_u32 s7, s7, 0
	s_add_u32 s98, s98, 0x8000
	s_addc_u32 s99, s99, 0
	v_pk_add_f32 v[62:63], v[62:63], v[130:131]
	v_pk_add_f32 v[64:65], v[64:65], v[132:133]
	v_pk_add_f32 v[58:59], v[58:59], v[134:135]
	v_pk_add_f32 v[60:61], v[60:61], v[136:137]
	v_mul_f32_e32 v146, 0xbfb8aa3b, v62
	v_mul_f32_e32 v147, 0xbfb8aa3b, v63
	v_mul_f32_e32 v148, 0xbfb8aa3b, v64
	v_mul_f32_e32 v149, 0xbfb8aa3b, v65
	v_mul_f32_e32 v150, 0xbfb8aa3b, v58
	v_mul_f32_e32 v151, 0xbfb8aa3b, v59
	v_mul_f32_e32 v152, 0xbfb8aa3b, v60
	v_mul_f32_e32 v153, 0xbfb8aa3b, v61
	v_exp_f32_e32 v146, v146
	v_exp_f32_e32 v147, v147
	v_exp_f32_e32 v148, v148
	v_exp_f32_e32 v149, v149
	v_exp_f32_e32 v150, v150
	v_exp_f32_e32 v151, v151
	v_exp_f32_e32 v152, v152
	v_exp_f32_e32 v153, v153
	s_waitcnt vmcnt(15)
	v_lshlrev_b32_e32 v62, 16, v192
	v_and_b32_e32 v63, 0xffff0000, v192
	v_lshlrev_b32_e32 v64, 16, v193
	v_and_b32_e32 v65, 0xffff0000, v193
	v_lshlrev_b32_e32 v58, 16, v194
	v_and_b32_e32 v59, 0xffff0000, v194
	v_lshlrev_b32_e32 v60, 16, v195
	v_and_b32_e32 v61, 0xffff0000, v195
	v_add_f32_e32 v146, 1.0, v146
	v_add_f32_e32 v147, 1.0, v147
	v_add_f32_e32 v148, 1.0, v148
	v_add_f32_e32 v149, 1.0, v149
	v_add_f32_e32 v150, 1.0, v150
	v_add_f32_e32 v151, 1.0, v151
	v_add_f32_e32 v152, 1.0, v152
	v_add_f32_e32 v153, 1.0, v153
	v_rcp_f32_e32 v146, v146
	v_rcp_f32_e32 v147, v147
	v_rcp_f32_e32 v148, v148
	v_rcp_f32_e32 v149, v149
	v_rcp_f32_e32 v150, v150
	v_rcp_f32_e32 v151, v151
	v_rcp_f32_e32 v152, v152
	v_rcp_f32_e32 v153, v153
	v_perm_b32 v154, v110, v110, s36
	v_perm_b32 v155, v110, v110, s37
	v_perm_b32 v156, v111, v111, s36
	v_perm_b32 v157, v111, v111, s37
	v_perm_b32 v158, v112, v112, s36
	v_perm_b32 v159, v112, v112, s37
	v_perm_b32 v160, v113, v113, s36
	v_perm_b32 v161, v113, v113, s37
	v_pk_fma_f32 v[146:147], v[146:147], v[62:63], v[154:155]
	v_pk_fma_f32 v[148:149], v[148:149], v[64:65], v[156:157]
	v_pk_fma_f32 v[150:151], v[150:151], v[58:59], v[158:159]
	v_pk_fma_f32 v[152:153], v[152:153], v[60:61], v[160:161]
	v_cvt_pk_bf16_f32 v162, v146, v147
	v_cvt_pk_bf16_f32 v163, v148, v149
	v_cvt_pk_bf16_f32 v164, v150, v151
	v_cvt_pk_bf16_f32 v165, v152, v153
	global_store_dwordx4 v212, v[162:165], s[100:101]
	global_load_dwordx4 v[174:177], v0, s[6:7]
	s_cmp_lt_u32 s77, 2
	s_cselect_b32 s0, s6, s98
	s_cselect_b32 s1, s7, s99
	global_load_dwordx4 v[86:89], v213, s[0:1]
	s_add_u32 s6, s6, 0x2000
	s_addc_u32 s7, s7, 0
	v_pk_add_f32 v[54:55], v[54:55], v[138:139]
	v_pk_add_f32 v[56:57], v[56:57], v[140:141]
	v_pk_add_f32 v[50:51], v[50:51], v[142:143]
	v_pk_add_f32 v[52:53], v[52:53], v[144:145]
	v_mul_f32_e32 v146, 0xbfb8aa3b, v54
	v_mul_f32_e32 v147, 0xbfb8aa3b, v55
	v_mul_f32_e32 v148, 0xbfb8aa3b, v56
	v_mul_f32_e32 v149, 0xbfb8aa3b, v57
	v_mul_f32_e32 v150, 0xbfb8aa3b, v50
	v_mul_f32_e32 v151, 0xbfb8aa3b, v51
	v_mul_f32_e32 v152, 0xbfb8aa3b, v52
	v_mul_f32_e32 v153, 0xbfb8aa3b, v53
	v_exp_f32_e32 v146, v146
	v_exp_f32_e32 v147, v147
	v_exp_f32_e32 v148, v148
	v_exp_f32_e32 v149, v149
	v_exp_f32_e32 v150, v150
	v_exp_f32_e32 v151, v151
	v_exp_f32_e32 v152, v152
	v_exp_f32_e32 v153, v153
	s_waitcnt vmcnt(15)
; DI unsigned pack2(float a, float b) { fv2 v = {a, b}; return __builtin_bit_cast(unsigned, __builtin_convertvector(v, bfv2)); }
; DI float bflo(unsigned u) { return __uint_as_float(u << 16); }
; DI float bfhi(unsigned u) { return __uint_as_float(u & 0xffff0000u); }
; DI float sigmoidf_(float x) { return __builtin_amdgcn_rcpf(1.f + __expf(-x)); }
;   DI void operator()(const f32x4 (&acc)[2][2][4][2], const Unit& u, int wr, int wc, int fr, int fq) const {
;     ...
; #pragma unroll
;         for (int mm = 0; mm < 2; ++mm)
; #pragma unroll
;           for (int bj = 0; bj < 2; ++bj) {
;             const int m = mp * 2 + mm;
;             const f32x4 g0 = acc[ai][bj][m][0] + bv[bj][0], g1 = acc[ai][bj][m][1] + bv[bj][1];
;             const u32x4 p_ = pv[mm][bj], o_ = ov[mm][bj];
;             u32x4 w;
;             w.x = pack2(bflo(o_.x) + sigmoidf_(g0[0]) * bflo(p_.x), bfhi(o_.x) + sigmoidf_(g0[1]) * bfhi(p_.x));
;             w.y = pack2(bflo(o_.y) + sigmoidf_(g0[2]) * bflo(p_.y), bfhi(o_.y) + sigmoidf_(g0[3]) * bfhi(p_.y));
;             w.z = pack2(bflo(o_.z) + sigmoidf_(g1[0]) * bflo(p_.z), bfhi(o_.z) + sigmoidf_(g1[1]) * bfhi(p_.z));
;             w.w = pack2(bflo(o_.w) + sigmoidf_(g1[2]) * bflo(p_.w), bfhi(o_.w) + sigmoidf_(g1[3]) * bfhi(p_.w));
;             *(u32x4*)(mixed + (size_t)(row0 + ai * HALF + m * 16) * 1024 + col0 + bj * HALF) = w;
;           }
;       }
	v_lshlrev_b32_e32 v54, 16, v106
	v_and_b32_e32 v55, 0xffff0000, v106
	v_lshlrev_b32_e32 v56, 16, v107
	v_and_b32_e32 v57, 0xffff0000, v107
	v_lshlrev_b32_e32 v50, 16, v108
	v_and_b32_e32 v51, 0xffff0000, v108
	v_lshlrev_b32_e32 v52, 16, v109
	v_and_b32_e32 v53, 0xffff0000, v109
	v_add_f32_e32 v146, 1.0, v146
	v_add_f32_e32 v147, 1.0, v147
	v_add_f32_e32 v148, 1.0, v148
	v_add_f32_e32 v149, 1.0, v149
	v_add_f32_e32 v150, 1.0, v150
	v_add_f32_e32 v151, 1.0, v151
	v_add_f32_e32 v152, 1.0, v152
	v_add_f32_e32 v153, 1.0, v153
	v_rcp_f32_e32 v146, v146
	v_rcp_f32_e32 v147, v147
	v_rcp_f32_e32 v148, v148
	v_rcp_f32_e32 v149, v149
	v_rcp_f32_e32 v150, v150
	v_rcp_f32_e32 v151, v151
	v_rcp_f32_e32 v152, v152
	v_rcp_f32_e32 v153, v153
	v_perm_b32 v154, v196, v196, s36
	v_perm_b32 v155, v196, v196, s37
	v_perm_b32 v156, v197, v197, s36
	v_perm_b32 v157, v197, v197, s37
	v_perm_b32 v158, v198, v198, s36
	v_perm_b32 v159, v198, v198, s37
	v_perm_b32 v160, v199, v199, s36
	v_perm_b32 v161, v199, v199, s37
	v_pk_fma_f32 v[146:147], v[146:147], v[54:55], v[154:155]
	v_pk_fma_f32 v[148:149], v[148:149], v[56:57], v[156:157]
	v_pk_fma_f32 v[150:151], v[150:151], v[50:51], v[158:159]
	v_pk_fma_f32 v[152:153], v[152:153], v[52:53], v[160:161]
	v_cvt_pk_bf16_f32 v162, v146, v147
	v_cvt_pk_bf16_f32 v163, v148, v149
	v_cvt_pk_bf16_f32 v164, v150, v151
	v_cvt_pk_bf16_f32 v165, v152, v153
	global_store_dwordx4 v212, v[162:165], s[100:101] offset:256
	s_add_u32 s100, s100, 0x8000
	s_addc_u32 s101, s101, 0
	global_load_dwordx4 v[82:85], v0, s[6:7]
	s_cmp_lt_u32 s77, 2
	s_cselect_b32 s0, s6, s98
	s_cselect_b32 s1, s7, s99
	global_load_dwordx4 v[184:187], v213, s[0:1] offset:256
	v_pk_add_f32 v[46:47], v[46:47], v[130:131]
	v_pk_add_f32 v[48:49], v[48:49], v[132:133]
	v_pk_add_f32 v[42:43], v[42:43], v[134:135]
	v_pk_add_f32 v[44:45], v[44:45], v[136:137]
	v_mul_f32_e32 v146, 0xbfb8aa3b, v46
	v_mul_f32_e32 v147, 0xbfb8aa3b, v47
	v_mul_f32_e32 v148, 0xbfb8aa3b, v48
	v_mul_f32_e32 v149, 0xbfb8aa3b, v49
	v_mul_f32_e32 v150, 0xbfb8aa3b, v42
	v_mul_f32_e32 v151, 0xbfb8aa3b, v43
	v_mul_f32_e32 v152, 0xbfb8aa3b, v44
	v_mul_f32_e32 v153, 0xbfb8aa3b, v45
	v_exp_f32_e32 v146, v146
	v_exp_f32_e32 v147, v147
	v_exp_f32_e32 v148, v148
	v_exp_f32_e32 v149, v149
	v_exp_f32_e32 v150, v150
	v_exp_f32_e32 v151, v151
	v_exp_f32_e32 v152, v152
	v_exp_f32_e32 v153, v153
	s_waitcnt vmcnt(15)
	v_lshlrev_b32_e32 v46, 16, v166
	v_and_b32_e32 v47, 0xffff0000, v166
	v_lshlrev_b32_e32 v48, 16, v167
	v_and_b32_e32 v49, 0xffff0000, v167
	v_lshlrev_b32_e32 v42, 16, v168
	v_and_b32_e32 v43, 0xffff0000, v168
	v_lshlrev_b32_e32 v44, 16, v169
	v_and_b32_e32 v45, 0xffff0000, v169
	v_add_f32_e32 v146, 1.0, v146
	v_add_f32_e32 v147, 1.0, v147
	v_add_f32_e32 v148, 1.0, v148
	v_add_f32_e32 v149, 1.0, v149
	v_add_f32_e32 v150, 1.0, v150
	v_add_f32_e32 v151, 1.0, v151
	v_add_f32_e32 v152, 1.0, v152
	v_add_f32_e32 v153, 1.0, v153
	v_rcp_f32_e32 v146, v146
	v_rcp_f32_e32 v147, v147
	v_rcp_f32_e32 v148, v148
	v_rcp_f32_e32 v149, v149
	v_rcp_f32_e32 v150, v150
	v_rcp_f32_e32 v151, v151
	v_rcp_f32_e32 v152, v152
	v_rcp_f32_e32 v153, v153
	v_perm_b32 v154, v102, v102, s36
	v_perm_b32 v155, v102, v102, s37
	v_perm_b32 v156, v103, v103, s36
	v_perm_b32 v157, v103, v103, s37
	v_perm_b32 v158, v104, v104, s36
	v_perm_b32 v159, v104, v104, s37
	v_perm_b32 v160, v105, v105, s36
	v_perm_b32 v161, v105, v105, s37
	v_pk_fma_f32 v[146:147], v[146:147], v[46:47], v[154:155]
	v_pk_fma_f32 v[148:149], v[148:149], v[48:49], v[156:157]
	v_pk_fma_f32 v[150:151], v[150:151], v[42:43], v[158:159]
	v_pk_fma_f32 v[152:153], v[152:153], v[44:45], v[160:161]
	v_cvt_pk_bf16_f32 v162, v146, v147
	v_cvt_pk_bf16_f32 v163, v148, v149
	v_cvt_pk_bf16_f32 v164, v150, v151
	v_cvt_pk_bf16_f32 v165, v152, v153
	global_store_dwordx4 v212, v[162:165], s[100:101]
	v_pk_add_f32 v[38:39], v[38:39], v[138:139]
	v_pk_add_f32 v[40:41], v[40:41], v[140:141]
	v_pk_add_f32 v[34:35], v[34:35], v[142:143]
	v_pk_add_f32 v[36:37], v[36:37], v[144:145]
	v_mul_f32_e32 v146, 0xbfb8aa3b, v38
	v_mul_f32_e32 v147, 0xbfb8aa3b, v39
	v_mul_f32_e32 v148, 0xbfb8aa3b, v40
	v_mul_f32_e32 v149, 0xbfb8aa3b, v41
	v_mul_f32_e32 v150, 0xbfb8aa3b, v34
	v_mul_f32_e32 v151, 0xbfb8aa3b, v35
	v_mul_f32_e32 v152, 0xbfb8aa3b, v36
	v_mul_f32_e32 v153, 0xbfb8aa3b, v37
	v_exp_f32_e32 v146, v146
	v_exp_f32_e32 v147, v147
	v_exp_f32_e32 v148, v148
	v_exp_f32_e32 v149, v149
	v_exp_f32_e32 v150, v150
	v_exp_f32_e32 v151, v151
	v_exp_f32_e32 v152, v152
	v_exp_f32_e32 v153, v153
	s_waitcnt vmcnt(13)
	v_lshlrev_b32_e32 v38, 16, v98
	v_and_b32_e32 v39, 0xffff0000, v98
	v_lshlrev_b32_e32 v40, 16, v99
	v_and_b32_e32 v41, 0xffff0000, v99
	v_lshlrev_b32_e32 v34, 16, v100
	v_and_b32_e32 v35, 0xffff0000, v100
	v_lshlrev_b32_e32 v36, 16, v101
	v_and_b32_e32 v37, 0xffff0000, v101
	v_add_f32_e32 v146, 1.0, v146
	v_add_f32_e32 v147, 1.0, v147
	v_add_f32_e32 v148, 1.0, v148
	v_add_f32_e32 v149, 1.0, v149
	v_add_f32_e32 v150, 1.0, v150
	v_add_f32_e32 v151, 1.0, v151
	v_add_f32_e32 v152, 1.0, v152
	v_add_f32_e32 v153, 1.0, v153
	v_rcp_f32_e32 v146, v146
	v_rcp_f32_e32 v147, v147
	v_rcp_f32_e32 v148, v148
	v_rcp_f32_e32 v149, v149
	v_rcp_f32_e32 v150, v150
	v_rcp_f32_e32 v151, v151
	v_rcp_f32_e32 v152, v152
	v_rcp_f32_e32 v153, v153
	v_perm_b32 v154, v170, v170, s36
	v_perm_b32 v155, v170, v170, s37
	v_perm_b32 v156, v171, v171, s36
	v_perm_b32 v157, v171, v171, s37
	v_perm_b32 v158, v172, v172, s36
	v_perm_b32 v159, v172, v172, s37
	v_perm_b32 v160, v173, v173, s36
	v_perm_b32 v161, v173, v173, s37
	v_pk_fma_f32 v[146:147], v[146:147], v[38:39], v[154:155]
	v_pk_fma_f32 v[148:149], v[148:149], v[40:41], v[156:157]
	v_pk_fma_f32 v[150:151], v[150:151], v[34:35], v[158:159]
	v_pk_fma_f32 v[152:153], v[152:153], v[36:37], v[160:161]
	v_cvt_pk_bf16_f32 v162, v146, v147
	v_cvt_pk_bf16_f32 v163, v148, v149
	v_cvt_pk_bf16_f32 v164, v150, v151
	v_cvt_pk_bf16_f32 v165, v152, v153
	global_store_dwordx4 v212, v[162:165], s[100:101] offset:256
	s_add_u32 s100, s100, 0x8000
	s_addc_u32 s101, s101, 0
	v_pk_add_f32 v[30:31], v[30:31], v[130:131]
	v_pk_add_f32 v[32:33], v[32:33], v[132:133]
	v_pk_add_f32 v[26:27], v[26:27], v[134:135]
	v_pk_add_f32 v[28:29], v[28:29], v[136:137]
	v_mul_f32_e32 v146, 0xbfb8aa3b, v30
	v_mul_f32_e32 v147, 0xbfb8aa3b, v31
	v_mul_f32_e32 v148, 0xbfb8aa3b, v32
	v_mul_f32_e32 v149, 0xbfb8aa3b, v33
	v_mul_f32_e32 v150, 0xbfb8aa3b, v26
	v_mul_f32_e32 v151, 0xbfb8aa3b, v27
	v_mul_f32_e32 v152, 0xbfb8aa3b, v28
	v_mul_f32_e32 v153, 0xbfb8aa3b, v29
	v_exp_f32_e32 v146, v146
	v_exp_f32_e32 v147, v147
	v_exp_f32_e32 v148, v148
	v_exp_f32_e32 v149, v149
	v_exp_f32_e32 v150, v150
	v_exp_f32_e32 v151, v151
	v_exp_f32_e32 v152, v152
	v_exp_f32_e32 v153, v153
	s_waitcnt vmcnt(11)
; DI unsigned pack2(float a, float b) { fv2 v = {a, b}; return __builtin_bit_cast(unsigned, __builtin_convertvector(v, bfv2)); }
; DI float bflo(unsigned u) { return __uint_as_float(u << 16); }
; DI float bfhi(unsigned u) { return __uint_as_float(u & 0xffff0000u); }
; DI float sigmoidf_(float x) { return __builtin_amdgcn_rcpf(1.f + __expf(-x)); }
;   DI void operator()(const f32x4 (&acc)[2][2][4][2], const Unit& u, int wr, int wc, int fr, int fq) const {
;     ...
; #pragma unroll
;         for (int mm = 0; mm < 2; ++mm)
; #pragma unroll
;           for (int bj = 0; bj < 2; ++bj) {
;             const int m = mp * 2 + mm;
;             const f32x4 g0 = acc[ai][bj][m][0] + bv[bj][0], g1 = acc[ai][bj][m][1] + bv[bj][1];
;             const u32x4 p_ = pv[mm][bj], o_ = ov[mm][bj];
;             u32x4 w;
;             w.x = pack2(bflo(o_.x) + sigmoidf_(g0[0]) * bflo(p_.x), bfhi(o_.x) + sigmoidf_(g0[1]) * bfhi(p_.x));
;             w.y = pack2(bflo(o_.y) + sigmoidf_(g0[2]) * bflo(p_.y), bfhi(o_.y) + sigmoidf_(g0[3]) * bfhi(p_.y));
;             w.z = pack2(bflo(o_.z) + sigmoidf_(g1[0]) * bflo(p_.z), bfhi(o_.z) + sigmoidf_(g1[1]) * bfhi(p_.z));
;             w.w = pack2(bflo(o_.w) + sigmoidf_(g1[2]) * bflo(p_.w), bfhi(o_.w) + sigmoidf_(g1[3]) * bfhi(p_.w));
;             *(u32x4*)(mixed + (size_t)(row0 + ai * HALF + m * 16) * 1024 + col0 + bj * HALF) = w;
;           }
;       }
	v_lshlrev_b32_e32 v30, 16, v126
	v_and_b32_e32 v31, 0xffff0000, v126
	v_lshlrev_b32_e32 v32, 16, v127
	v_and_b32_e32 v33, 0xffff0000, v127
	v_lshlrev_b32_e32 v26, 16, v128
	v_and_b32_e32 v27, 0xffff0000, v128
	v_lshlrev_b32_e32 v28, 16, v129
	v_and_b32_e32 v29, 0xffff0000, v129
	v_add_f32_e32 v146, 1.0, v146
	v_add_f32_e32 v147, 1.0, v147
	v_add_f32_e32 v148, 1.0, v148
	v_add_f32_e32 v149, 1.0, v149
	v_add_f32_e32 v150, 1.0, v150
	v_add_f32_e32 v151, 1.0, v151
	v_add_f32_e32 v152, 1.0, v152
	v_add_f32_e32 v153, 1.0, v153
	v_rcp_f32_e32 v146, v146
	v_rcp_f32_e32 v147, v147
	v_rcp_f32_e32 v148, v148
	v_rcp_f32_e32 v149, v149
	v_rcp_f32_e32 v150, v150
	v_rcp_f32_e32 v151, v151
	v_rcp_f32_e32 v152, v152
	v_rcp_f32_e32 v153, v153
	v_perm_b32 v154, v94, v94, s36
	v_perm_b32 v155, v94, v94, s37
	v_perm_b32 v156, v95, v95, s36
	v_perm_b32 v157, v95, v95, s37
	v_perm_b32 v158, v96, v96, s36
	v_perm_b32 v159, v96, v96, s37
	v_perm_b32 v160, v97, v97, s36
	v_perm_b32 v161, v97, v97, s37
	v_pk_fma_f32 v[146:147], v[146:147], v[30:31], v[154:155]
	v_pk_fma_f32 v[148:149], v[148:149], v[32:33], v[156:157]
	v_pk_fma_f32 v[150:151], v[150:151], v[26:27], v[158:159]
	v_pk_fma_f32 v[152:153], v[152:153], v[28:29], v[160:161]
	v_cvt_pk_bf16_f32 v162, v146, v147
	v_cvt_pk_bf16_f32 v163, v148, v149
	v_cvt_pk_bf16_f32 v164, v150, v151
	v_cvt_pk_bf16_f32 v165, v152, v153
	global_store_dwordx4 v212, v[162:165], s[100:101]
	v_pk_add_f32 v[22:23], v[22:23], v[138:139]
	v_pk_add_f32 v[24:25], v[24:25], v[140:141]
	v_pk_add_f32 v[18:19], v[18:19], v[142:143]
	v_pk_add_f32 v[20:21], v[20:21], v[144:145]
	v_mul_f32_e32 v146, 0xbfb8aa3b, v22
	v_mul_f32_e32 v147, 0xbfb8aa3b, v23
	v_mul_f32_e32 v148, 0xbfb8aa3b, v24
	v_mul_f32_e32 v149, 0xbfb8aa3b, v25
	v_mul_f32_e32 v150, 0xbfb8aa3b, v18
	v_mul_f32_e32 v151, 0xbfb8aa3b, v19
	v_mul_f32_e32 v152, 0xbfb8aa3b, v20
	v_mul_f32_e32 v153, 0xbfb8aa3b, v21
	v_exp_f32_e32 v146, v146
	v_exp_f32_e32 v147, v147
	v_exp_f32_e32 v148, v148
	v_exp_f32_e32 v149, v149
	v_exp_f32_e32 v150, v150
	v_exp_f32_e32 v151, v151
	v_exp_f32_e32 v152, v152
	v_exp_f32_e32 v153, v153
	s_waitcnt vmcnt(9)
	v_lshlrev_b32_e32 v22, 16, v90
	v_and_b32_e32 v23, 0xffff0000, v90
	v_lshlrev_b32_e32 v24, 16, v91
	v_and_b32_e32 v25, 0xffff0000, v91
	v_lshlrev_b32_e32 v18, 16, v92
	v_and_b32_e32 v19, 0xffff0000, v92
	v_lshlrev_b32_e32 v20, 16, v93
	v_and_b32_e32 v21, 0xffff0000, v93
	v_add_f32_e32 v146, 1.0, v146
	v_add_f32_e32 v147, 1.0, v147
	v_add_f32_e32 v148, 1.0, v148
	v_add_f32_e32 v149, 1.0, v149
	v_add_f32_e32 v150, 1.0, v150
	v_add_f32_e32 v151, 1.0, v151
	v_add_f32_e32 v152, 1.0, v152
	v_add_f32_e32 v153, 1.0, v153
	v_rcp_f32_e32 v146, v146
	v_rcp_f32_e32 v147, v147
	v_rcp_f32_e32 v148, v148
	v_rcp_f32_e32 v149, v149
	v_rcp_f32_e32 v150, v150
	v_rcp_f32_e32 v151, v151
	v_rcp_f32_e32 v152, v152
	v_rcp_f32_e32 v153, v153
	v_perm_b32 v154, v122, v122, s36
	v_perm_b32 v155, v122, v122, s37
	v_perm_b32 v156, v123, v123, s36
	v_perm_b32 v157, v123, v123, s37
	v_perm_b32 v158, v124, v124, s36
	v_perm_b32 v159, v124, v124, s37
	v_perm_b32 v160, v125, v125, s36
	v_perm_b32 v161, v125, v125, s37
	v_pk_fma_f32 v[146:147], v[146:147], v[22:23], v[154:155]
	v_pk_fma_f32 v[148:149], v[148:149], v[24:25], v[156:157]
	v_pk_fma_f32 v[150:151], v[150:151], v[18:19], v[158:159]
	v_pk_fma_f32 v[152:153], v[152:153], v[20:21], v[160:161]
	v_cvt_pk_bf16_f32 v162, v146, v147
	v_cvt_pk_bf16_f32 v163, v148, v149
	v_cvt_pk_bf16_f32 v164, v150, v151
	v_cvt_pk_bf16_f32 v165, v152, v153
	global_store_dwordx4 v212, v[162:165], s[100:101] offset:256
	s_add_u32 s100, s100, 0x8000
	s_addc_u32 s101, s101, 0
	v_pk_add_f32 v[14:15], v[14:15], v[130:131]
	v_pk_add_f32 v[16:17], v[16:17], v[132:133]
	v_pk_add_f32 v[10:11], v[10:11], v[134:135]
	v_pk_add_f32 v[12:13], v[12:13], v[136:137]
	v_mul_f32_e32 v146, 0xbfb8aa3b, v14
	v_mul_f32_e32 v147, 0xbfb8aa3b, v15
	v_mul_f32_e32 v148, 0xbfb8aa3b, v16
	v_mul_f32_e32 v149, 0xbfb8aa3b, v17
	v_mul_f32_e32 v150, 0xbfb8aa3b, v10
	v_mul_f32_e32 v151, 0xbfb8aa3b, v11
	v_mul_f32_e32 v152, 0xbfb8aa3b, v12
	v_mul_f32_e32 v153, 0xbfb8aa3b, v13
	v_exp_f32_e32 v146, v146
	v_exp_f32_e32 v147, v147
	v_exp_f32_e32 v148, v148
	v_exp_f32_e32 v149, v149
	v_exp_f32_e32 v150, v150
	v_exp_f32_e32 v151, v151
	v_exp_f32_e32 v152, v152
	v_exp_f32_e32 v153, v153
	s_waitcnt vmcnt(7)
; DI unsigned pack2(float a, float b) { fv2 v = {a, b}; return __builtin_bit_cast(unsigned, __builtin_convertvector(v, bfv2)); }
; DI float bflo(unsigned u) { return __uint_as_float(u << 16); }
; DI float bfhi(unsigned u) { return __uint_as_float(u & 0xffff0000u); }
; DI float sigmoidf_(float x) { return __builtin_amdgcn_rcpf(1.f + __expf(-x)); }
;   DI void operator()(const f32x4 (&acc)[2][2][4][2], const Unit& u, int wr, int wc, int fr, int fq) const {
;     ...
; #pragma unroll
;         for (int mm = 0; mm < 2; ++mm)
; #pragma unroll
;           for (int bj = 0; bj < 2; ++bj) {
;             const int m = mp * 2 + mm;
;             const f32x4 g0 = acc[ai][bj][m][0] + bv[bj][0], g1 = acc[ai][bj][m][1] + bv[bj][1];
;             const u32x4 p_ = pv[mm][bj], o_ = ov[mm][bj];
;             u32x4 w;
;             w.x = pack2(bflo(o_.x) + sigmoidf_(g0[0]) * bflo(p_.x), bfhi(o_.x) + sigmoidf_(g0[1]) * bfhi(p_.x));
;             w.y = pack2(bflo(o_.y) + sigmoidf_(g0[2]) * bflo(p_.y), bfhi(o_.y) + sigmoidf_(g0[3]) * bfhi(p_.y));
;             w.z = pack2(bflo(o_.z) + sigmoidf_(g1[0]) * bflo(p_.z), bfhi(o_.z) + sigmoidf_(g1[1]) * bfhi(p_.z));
;             w.w = pack2(bflo(o_.w) + sigmoidf_(g1[2]) * bflo(p_.w), bfhi(o_.w) + sigmoidf_(g1[3]) * bfhi(p_.w));
;             *(u32x4*)(mixed + (size_t)(row0 + ai * HALF + m * 16) * 1024 + col0 + bj * HALF) = w;
;           }
;       }
	v_lshlrev_b32_e32 v14, 16, v174
	v_and_b32_e32 v15, 0xffff0000, v174
	v_lshlrev_b32_e32 v16, 16, v175
	v_and_b32_e32 v17, 0xffff0000, v175
	v_lshlrev_b32_e32 v10, 16, v176
	v_and_b32_e32 v11, 0xffff0000, v176
	v_lshlrev_b32_e32 v12, 16, v177
	v_and_b32_e32 v13, 0xffff0000, v177
	v_add_f32_e32 v146, 1.0, v146
	v_add_f32_e32 v147, 1.0, v147
	v_add_f32_e32 v148, 1.0, v148
	v_add_f32_e32 v149, 1.0, v149
	v_add_f32_e32 v150, 1.0, v150
	v_add_f32_e32 v151, 1.0, v151
	v_add_f32_e32 v152, 1.0, v152
	v_add_f32_e32 v153, 1.0, v153
	v_rcp_f32_e32 v146, v146
	v_rcp_f32_e32 v147, v147
	v_rcp_f32_e32 v148, v148
	v_rcp_f32_e32 v149, v149
	v_rcp_f32_e32 v150, v150
	v_rcp_f32_e32 v151, v151
	v_rcp_f32_e32 v152, v152
	v_rcp_f32_e32 v153, v153
	v_perm_b32 v154, v86, v86, s36
	v_perm_b32 v155, v86, v86, s37
	v_perm_b32 v156, v87, v87, s36
	v_perm_b32 v157, v87, v87, s37
	v_perm_b32 v158, v88, v88, s36
	v_perm_b32 v159, v88, v88, s37
	v_perm_b32 v160, v89, v89, s36
	v_perm_b32 v161, v89, v89, s37
	v_pk_fma_f32 v[146:147], v[146:147], v[14:15], v[154:155]
	v_pk_fma_f32 v[148:149], v[148:149], v[16:17], v[156:157]
	v_pk_fma_f32 v[150:151], v[150:151], v[10:11], v[158:159]
	v_pk_fma_f32 v[152:153], v[152:153], v[12:13], v[160:161]
	v_cvt_pk_bf16_f32 v162, v146, v147
	v_cvt_pk_bf16_f32 v163, v148, v149
	v_cvt_pk_bf16_f32 v164, v150, v151
	v_cvt_pk_bf16_f32 v165, v152, v153
	global_store_dwordx4 v212, v[162:165], s[100:101]
	v_pk_add_f32 v[6:7], v[6:7], v[138:139]
	v_pk_add_f32 v[8:9], v[8:9], v[140:141]
	v_pk_add_f32 v[2:3], v[2:3], v[142:143]
	v_pk_add_f32 v[4:5], v[4:5], v[144:145]
	v_mul_f32_e32 v146, 0xbfb8aa3b, v6
	v_mul_f32_e32 v147, 0xbfb8aa3b, v7
	v_mul_f32_e32 v148, 0xbfb8aa3b, v8
	v_mul_f32_e32 v149, 0xbfb8aa3b, v9
	v_mul_f32_e32 v150, 0xbfb8aa3b, v2
	v_mul_f32_e32 v151, 0xbfb8aa3b, v3
	v_mul_f32_e32 v152, 0xbfb8aa3b, v4
	v_mul_f32_e32 v153, 0xbfb8aa3b, v5
	v_exp_f32_e32 v146, v146
	v_exp_f32_e32 v147, v147
	v_exp_f32_e32 v148, v148
	v_exp_f32_e32 v149, v149
	v_exp_f32_e32 v150, v150
	v_exp_f32_e32 v151, v151
	v_exp_f32_e32 v152, v152
	v_exp_f32_e32 v153, v153
	s_waitcnt vmcnt(5)
	v_lshlrev_b32_e32 v6, 16, v82
	v_and_b32_e32 v7, 0xffff0000, v82
	v_lshlrev_b32_e32 v8, 16, v83
	v_and_b32_e32 v9, 0xffff0000, v83
	v_lshlrev_b32_e32 v2, 16, v84
	v_and_b32_e32 v3, 0xffff0000, v84
	v_lshlrev_b32_e32 v4, 16, v85
	v_and_b32_e32 v5, 0xffff0000, v85
	v_add_f32_e32 v146, 1.0, v146
	v_add_f32_e32 v147, 1.0, v147
	v_add_f32_e32 v148, 1.0, v148
	v_add_f32_e32 v149, 1.0, v149
	v_add_f32_e32 v150, 1.0, v150
	v_add_f32_e32 v151, 1.0, v151
	v_add_f32_e32 v152, 1.0, v152
	v_add_f32_e32 v153, 1.0, v153
	v_rcp_f32_e32 v146, v146
	v_rcp_f32_e32 v147, v147
	v_rcp_f32_e32 v148, v148
	v_rcp_f32_e32 v149, v149
	v_rcp_f32_e32 v150, v150
	v_rcp_f32_e32 v151, v151
	v_rcp_f32_e32 v152, v152
	v_rcp_f32_e32 v153, v153
	v_perm_b32 v154, v184, v184, s36
	v_perm_b32 v155, v184, v184, s37
	v_perm_b32 v156, v185, v185, s36
	v_perm_b32 v157, v185, v185, s37
	v_perm_b32 v158, v186, v186, s36
	v_perm_b32 v159, v186, v186, s37
	v_perm_b32 v160, v187, v187, s36
	v_perm_b32 v161, v187, v187, s37
	v_pk_fma_f32 v[146:147], v[146:147], v[6:7], v[154:155]
	v_pk_fma_f32 v[148:149], v[148:149], v[8:9], v[156:157]
	v_pk_fma_f32 v[150:151], v[150:151], v[2:3], v[158:159]
	v_pk_fma_f32 v[152:153], v[152:153], v[4:5], v[160:161]
	v_cvt_pk_bf16_f32 v162, v146, v147
	v_cvt_pk_bf16_f32 v163, v148, v149
	v_cvt_pk_bf16_f32 v164, v150, v151
	v_cvt_pk_bf16_f32 v165, v152, v153
	global_store_dwordx4 v212, v[162:165], s[100:101] offset:256
	s_branch .LBB0_930
